# v73 + norm2 context-row split-K partial sum: 20 loads issued up front (was 4 staged batches)
# speedup vs baseline: 1.0064x; 1.0064x over previous
.LBB0_532:
	s_or_b64 exec, exec, s[34:35]
	v_add_u32_e32 v86, s4, v66
	v_min_i32_e32 v10, 0x87ff, v86
	v_ashrrev_i32_e32 v11, 31, v10
	v_add_u32_e32 v0, 0xffff8000, v10
	v_cmp_gt_i32_e32 vcc, s40, v86
	v_mov_b32_e32 v12, s55
	v_mov_b32_e32 v13, s48
	v_cndmask_b32_e32 v11, 0, v11, vcc
	v_cndmask_b32_e32 v10, v0, v10, vcc
	v_cndmask_b32_e32 v13, v12, v13, vcc
	v_mov_b32_e32 v12, s54
	v_mov_b32_e32 v14, s49
	v_cndmask_b32_e32 v12, v12, v14, vcc
	v_lshlrev_b64 v[10:11], 12, v[10:11]
	v_lshl_add_u64 v[10:11], v[12:13], 0, v[10:11]
	v_lshl_add_u64 v[10:11], v[10:11], 0, v[78:79]
	global_load_dwordx4 v[34:37], v[10:11], off nt
	global_load_dwordx4 v[30:33], v[10:11], off offset:1024 nt
	global_load_dwordx4 v[18:21], v[10:11], off offset:2048 nt
	s_nop 0
	global_load_dwordx4 v[10:13], v[10:11], off offset:3072 nt
	v_cmp_lt_i32_e32 vcc, s14, v86
	s_mov_b32 s8, 0x8800
	v_cmp_gt_i32_e64 s[8:9], s8, v86
	s_and_b64 vcc, vcc, s[8:9]
	s_and_b64 s[8:9], s[22:23], vcc
	s_and_saveexec_b64 s[34:35], s[8:9]
	s_cbranch_execz .LBB0_542
	v_readlane_b32 s8, v253, 18
	v_lshlrev_b64 v[14:15], 12, v[0:1]
	v_readlane_b32 s9, v253, 19
	v_mov_b32_e32 v79, v1
	v_cmp_gt_u32_e32 vcc, s15, v86
	v_lshl_add_u64 v[42:43], s[8:9], 0, v[14:15]
	s_mov_b64 s[8:9], 0x800000
	v_lshl_add_u64 v[28:29], v[42:43], 0, s[8:9]
	s_mov_b64 s[8:9], 0x1000000
	v_lshl_add_u64 v[26:27], v[42:43], 0, s[8:9]
	s_mov_b64 s[8:9], 0x1800000
	v_lshl_add_u64 v[16:17], v[42:43], 0, s[8:9]
	v_lshl_add_u64 v[42:43], v[42:43], 0, v[78:79]
	v_lshl_add_u64 v[28:29], v[28:29], 0, v[78:79]
	v_lshl_add_u64 v[26:27], v[26:27], 0, v[78:79]
	v_lshl_add_u64 v[16:17], v[16:17], 0, v[78:79]
	v_lshl_add_u64 v[14:15], s[54:55], 0, v[14:15]
	v_lshl_add_u64 v[44:45], v[14:15], 0, v[78:79]
	global_load_dwordx4 v[118:121], v[42:43], off
	global_load_dwordx4 v[122:125], v[28:29], off
	global_load_dwordx4 v[126:129], v[26:27], off
	global_load_dwordx4 v[130:133], v[16:17], off
	global_load_dwordx4 v[204:207], v[68:69], off
	global_load_dwordx4 v[134:137], v[42:43], off offset:1024
	global_load_dwordx4 v[138:141], v[28:29], off offset:1024
	global_load_dwordx4 v[142:145], v[26:27], off offset:1024
	global_load_dwordx4 v[146:149], v[16:17], off offset:1024
	global_load_dwordx4 v[208:211], v[68:69], off offset:1024
	global_load_dwordx4 v[150:153], v[42:43], off offset:2048
	global_load_dwordx4 v[176:179], v[28:29], off offset:2048
	global_load_dwordx4 v[180:183], v[26:27], off offset:2048
	global_load_dwordx4 v[184:187], v[16:17], off offset:2048
	global_load_dwordx4 v[88:91], v[68:69], off offset:2048
	global_load_dwordx4 v[188:191], v[42:43], off offset:3072
	global_load_dwordx4 v[192:195], v[28:29], off offset:3072
	global_load_dwordx4 v[196:199], v[26:27], off offset:3072
	global_load_dwordx4 v[200:203], v[16:17], off offset:3072
	global_load_dwordx4 v[92:95], v[68:69], off offset:3072
	s_waitcnt vmcnt(15)
	v_pk_add_f32 v[120:121], v[120:121], v[124:125]
	v_pk_add_f32 v[118:119], v[118:119], v[122:123]
	v_pk_add_f32 v[120:121], v[120:121], v[128:129]
	v_pk_add_f32 v[118:119], v[118:119], v[126:127]
	v_pk_add_f32 v[120:121], v[120:121], v[132:133]
	v_pk_add_f32 v[118:119], v[118:119], v[130:131]
	v_pk_fma_f32 v[36:37], v[120:121], v[206:207], v[36:37]
	v_pk_fma_f32 v[34:35], v[118:119], v[204:205], v[34:35]
	s_and_saveexec_b64 s[36:37], vcc
	global_store_dwordx4 v[44:45], v[34:37], off
	s_or_b64 exec, exec, s[36:37]
	s_waitcnt vmcnt(10)
	v_pk_add_f32 v[136:137], v[136:137], v[140:141]
	v_pk_add_f32 v[134:135], v[134:135], v[138:139]
	v_pk_add_f32 v[136:137], v[136:137], v[144:145]
	v_pk_add_f32 v[134:135], v[134:135], v[142:143]
	v_pk_add_f32 v[136:137], v[136:137], v[148:149]
	v_pk_add_f32 v[134:135], v[134:135], v[146:147]
	v_pk_fma_f32 v[32:33], v[136:137], v[210:211], v[32:33]
	v_pk_fma_f32 v[30:31], v[134:135], v[208:209], v[30:31]
	s_and_saveexec_b64 s[36:37], vcc
	global_store_dwordx4 v[44:45], v[30:33], off offset:1024
	s_or_b64 exec, exec, s[36:37]
	s_waitcnt vmcnt(5)
	v_pk_add_f32 v[152:153], v[152:153], v[178:179]
	v_pk_add_f32 v[150:151], v[150:151], v[176:177]
	v_pk_add_f32 v[152:153], v[152:153], v[182:183]
	v_pk_add_f32 v[150:151], v[150:151], v[180:181]
	v_pk_add_f32 v[152:153], v[152:153], v[186:187]
	v_pk_add_f32 v[150:151], v[150:151], v[184:185]
	v_pk_fma_f32 v[20:21], v[152:153], v[90:91], v[20:21]
	v_pk_fma_f32 v[18:19], v[150:151], v[88:89], v[18:19]
	s_and_saveexec_b64 s[36:37], vcc
	global_store_dwordx4 v[44:45], v[18:21], off offset:2048
	s_or_b64 exec, exec, s[36:37]
	s_waitcnt vmcnt(0)
	v_pk_add_f32 v[190:191], v[190:191], v[194:195]
	v_pk_add_f32 v[188:189], v[188:189], v[192:193]
	v_pk_add_f32 v[190:191], v[190:191], v[198:199]
	v_pk_add_f32 v[188:189], v[188:189], v[196:197]
	v_pk_add_f32 v[190:191], v[190:191], v[202:203]
	v_pk_add_f32 v[188:189], v[188:189], v[200:201]
	v_pk_fma_f32 v[12:13], v[190:191], v[94:95], v[12:13]
	v_pk_fma_f32 v[10:11], v[188:189], v[92:93], v[10:11]
	s_and_saveexec_b64 s[36:37], vcc
	global_store_dwordx4 v[44:45], v[10:13], off offset:3072
	s_or_b64 exec, exec, s[36:37]

.LBB0_567:
	v_min_i32_e32 v0, 0x8000, v90
	v_ashrrev_i32_e32 v0, 12, v0
	v_mul_i32_i24_e32 v2, 0x1800, v0
	v_ashrrev_i32_e32 v3, 31, v2
	v_lshl_add_u64 v[10:11], v[2:3], 2, s[44:45]
	v_lshl_add_u64 v[14:15], v[10:11], 0, s[8:9]
	v_mov_b32_e32 v79, v1
	v_lshl_add_u64 v[6:7], v[14:15], 0, v[78:79]
	global_load_dwordx4 v[2:5], v[70:71], off
	v_lshl_add_u64 v[16:17], v[10:11], 0, v[78:79]
	global_load_dwordx4 v[6:9], v[6:7], off
	v_mul_f32_e32 v0, v63, v63
	global_load_dwordx4 v[10:13], v[16:17], off
	v_mov_b32_e32 v81, v1
	v_mov_b32_e32 v83, v1
	v_mov_b32_e32 v85, v1
	global_load_dwordx4 v[168:171], v[70:71], off offset:1024
	v_lshl_add_u64 v[172:173], v[14:15], 0, v[80:81]
	global_load_dwordx4 v[172:175], v[172:173], off
	global_load_dwordx4 v[176:179], v[16:17], off offset:1024
	global_load_dwordx4 v[180:183], v[70:71], off offset:2048
	v_lshl_add_u64 v[184:185], v[14:15], 0, v[82:83]
	global_load_dwordx4 v[184:187], v[184:185], off
	global_load_dwordx4 v[188:191], v[16:17], off offset:2048
	global_load_dwordx4 v[192:195], v[70:71], off offset:3072
	v_lshl_add_u64 v[196:197], v[14:15], 0, v[84:85]
	global_load_dwordx4 v[196:199], v[196:197], off
	global_load_dwordx4 v[200:203], v[16:17], off offset:3072
	v_mul_f32_e32 v18, v59, v59
	v_mul_f32_e32 v19, v55, v55
	v_fmac_f32_e32 v0, v62, v62
	v_fmac_f32_e32 v18, v58, v58
	v_mul_f32_e32 v20, v51, v51
	v_fmac_f32_e32 v19, v54, v54
	v_fmac_f32_e32 v0, v64, v64
	v_fmac_f32_e32 v18, v60, v60
	v_fmac_f32_e32 v20, v50, v50
	v_fmac_f32_e32 v19, v56, v56
	v_fmac_f32_e32 v0, v65, v65
	v_fmac_f32_e32 v18, v61, v61
	v_fmac_f32_e32 v20, v52, v52
	v_fmac_f32_e32 v19, v57, v57
	v_add_f32_e32 v0, v18, v0
	v_fmac_f32_e32 v20, v53, v53
	v_add_f32_e32 v0, v19, v0
	v_add_f32_e32 v0, v20, v0
	ds_bpermute_b32 v18, v102, v0
	v_ashrrev_i32_e32 v91, 31, v90
	v_mov_b32_e32 v81, v1
	v_mov_b32_e32 v83, v1
	v_mov_b32_e32 v85, v1
	s_waitcnt lgkmcnt(0)
	v_add_f32_e32 v0, v0, v18
	ds_bpermute_b32 v18, v103, v0
	s_waitcnt lgkmcnt(0)
	v_add_f32_e32 v0, v0, v18
	ds_bpermute_b32 v18, v104, v0
	s_waitcnt lgkmcnt(0)
	v_add_f32_e32 v0, v0, v18
	ds_bpermute_b32 v18, v105, v0
	s_waitcnt lgkmcnt(0)
	v_add_f32_e32 v0, v0, v18
	ds_bpermute_b32 v18, v106, v0
	s_waitcnt lgkmcnt(0)
	v_add_f32_e32 v0, v0, v18
	ds_bpermute_b32 v18, v107, v0
	s_waitcnt lgkmcnt(0)
	v_add_f32_e32 v0, v0, v18
	v_fmamk_f32 v0, v0, 0x3a800000, v218
	v_mul_f32_e32 v18, 0x4b800000, v0
	v_cmp_gt_f32_e32 vcc, s13, v0
	s_waitcnt vmcnt(10)
	v_pk_add_f32 v[8:9], v[8:9], 1.0 op_sel_hi:[1,0]
	v_cndmask_b32_e32 v0, v0, v18, vcc
	v_rsq_f32_e32 v0, v0
	v_pk_add_f32 v[6:7], v[6:7], 1.0 op_sel_hi:[1,0]
	v_lshlrev_b64 v[18:19], 11, v[90:91]
	v_lshl_add_u64 v[18:19], v[74:75], 0, v[18:19]
	v_mul_f32_e32 v20, 0x45800000, v0
	v_cndmask_b32_e32 v0, v0, v20, vcc
	v_pk_mul_f32 v[20:21], v[64:65], v[0:1] op_sel_hi:[1,0]
	v_pk_mul_f32 v[22:23], v[62:63], v[0:1] op_sel_hi:[1,0]
	v_pk_mul_f32 v[4:5], v[4:5], v[20:21]
	v_pk_mul_f32 v[2:3], v[2:3], v[22:23]
	s_waitcnt vmcnt(9)
	v_pk_fma_f32 v[4:5], v[8:9], v[4:5], v[12:13]
	v_pk_fma_f32 v[2:3], v[6:7], v[2:3], v[10:11]
	v_lshl_add_u64 v[6:7], v[14:15], 0, v[80:81]
	v_cvt_pk_bf16_f32 v2, v2, v3
	v_cvt_pk_bf16_f32 v3, v4, v5
	global_store_dwordx2 v[18:19], v[2:3], off
	v_pk_mul_f32 v[20:21], v[60:61], v[0:1] op_sel_hi:[1,0]
	v_pk_mul_f32 v[22:23], v[58:59], v[0:1] op_sel_hi:[1,0]
	s_waitcnt vmcnt(7)
	v_pk_add_f32 v[8:9], v[174:175], 1.0 op_sel_hi:[1, 0]
	v_pk_mul_f32 v[2:3], v[168:169], v[22:23]
	v_pk_mul_f32 v[4:5], v[170:171], v[20:21]
	v_pk_add_f32 v[6:7], v[172:173], 1.0 op_sel_hi:[1, 0]
	v_pk_fma_f32 v[4:5], v[8:9], v[4:5], v[178:179]
	v_pk_fma_f32 v[2:3], v[6:7], v[2:3], v[176:177]
	v_lshl_add_u64 v[6:7], v[14:15], 0, v[82:83]
	v_cvt_pk_bf16_f32 v2, v2, v3
	v_cvt_pk_bf16_f32 v3, v4, v5
	global_store_dwordx2 v[18:19], v[2:3], off offset:512
	v_pk_mul_f32 v[20:21], v[56:57], v[0:1] op_sel_hi:[1,0]
	v_pk_mul_f32 v[22:23], v[54:55], v[0:1] op_sel_hi:[1,0]
	s_waitcnt vmcnt(5)
	v_pk_add_f32 v[8:9], v[186:187], 1.0 op_sel_hi:[1, 0]
	v_pk_mul_f32 v[2:3], v[180:181], v[22:23]
	v_pk_mul_f32 v[4:5], v[182:183], v[20:21]
	v_pk_add_f32 v[6:7], v[184:185], 1.0 op_sel_hi:[1, 0]
	v_pk_fma_f32 v[4:5], v[8:9], v[4:5], v[190:191]
	v_pk_fma_f32 v[2:3], v[6:7], v[2:3], v[188:189]
	v_lshl_add_u64 v[6:7], v[14:15], 0, v[84:85]
	v_cvt_pk_bf16_f32 v2, v2, v3
	v_cvt_pk_bf16_f32 v3, v4, v5
	global_store_dwordx2 v[18:19], v[2:3], off offset:1024
	v_pk_mul_f32 v[14:15], v[52:53], v[0:1] op_sel_hi:[1,0]
	v_pk_mul_f32 v[16:17], v[50:51], v[0:1] op_sel_hi:[1,0]
	s_waitcnt vmcnt(3)
	v_pk_add_f32 v[8:9], v[198:199], 1.0 op_sel_hi:[1, 0]
	v_pk_mul_f32 v[2:3], v[16:17], v[192:193]
	v_pk_mul_f32 v[4:5], v[14:15], v[194:195]
	v_pk_add_f32 v[6:7], v[196:197], 1.0 op_sel_hi:[1, 0]
	v_pk_fma_f32 v[4:5], v[4:5], v[8:9], v[202:203]
	v_pk_fma_f32 v[2:3], v[2:3], v[6:7], v[200:201]
	s_nop 0
	v_cvt_pk_bf16_f32 v2, v2, v3
	v_cvt_pk_bf16_f32 v3, v4, v5
	global_store_dwordx2 v[18:19], v[2:3], off offset:1536
	s_branch .LBB0_529
	s_nop 0
	s_nop 0
	s_nop 0
	s_nop 0
	s_nop 0
	s_nop 0
	s_nop 0
	s_nop 0
	s_nop 0
	s_nop 0
	s_nop 0
	s_nop 0
	s_nop 0
	s_nop 0
	s_nop 0
	s_nop 0
	s_nop 0
	s_nop 0
	s_nop 0
	s_nop 0
	s_nop 0
	s_nop 0
	s_nop 0
	s_nop 0
	s_nop 0
	s_nop 0
	s_nop 0
	s_nop 0
	s_nop 0
	s_nop 0
	s_nop 0
	s_nop 0
	s_nop 0
	s_nop 0
	s_nop 0
	s_nop 0
	s_nop 0
	s_nop 0
	s_nop 0
	s_nop 0
	s_nop 0
	s_nop 0
	s_nop 0
	s_nop 0
	s_nop 0
	s_nop 0
	s_nop 0
	s_nop 0
	s_nop 0
